# FFN-up next-tile index: shift/mask fast path when the row-group size is 8 (all but the last group), generic division kept for the tail
# speedup vs baseline: 1.0078x; 1.0017x over previous
;     __device__ bool next(int i, Unit& u) const {
;         const long L = (long)i * G + c; if (L >= nwg) return false;
;         int wgid = (int)L; { const int q = nwg / NXCD, r = nwg % NXCD, xcd = wgid % NXCD, off = wgid / NXCD; wgid = (xcd < r ? xcd * (q + 1) : r * (q + 1) + (xcd - r) * q) + off; }
;         const int nig = WGM * nN, gid = wgid / nig, fm = gid * WGM, gsz = (nM - fm) < WGM ? (nM - fm) : WGM;
;         u.pm = fm + ((wgid % nig) % gsz); u.pn = (wgid % nig) / gsz; return true;
;     }
.LBB0_782:
	s_ashr_i32 s14, s17, 3
	s_add_i32 s14, s18, s14
	s_mul_hi_i32 s15, s14, 0x2e8ba2e9
	s_lshr_b32 s16, s15, 31
	s_ashr_i32 s15, s15, 5
	s_add_i32 s15, s15, s16
	s_lshl_b32 s16, s15, 3
	s_sub_i32 s17, 0x109, s16
	s_min_i32 s17, s17, 8
	s_mulk_i32 s15, 0xb0
	s_sub_i32 s15, s14, s15
	s_cmp_lg_u32 s17, 8
	s_cbranch_scc1 .Lup_gsz_generic
	s_lshr_b32 s14, s15, 3
	s_and_b32 s15, s15, 7
	s_add_i32 s30, s16, s15
	s_branch .LBB0_783
.Lup_gsz_generic:
	s_abs_i32 s18, s17
	v_cvt_f32_u32_e32 v2, s18
	s_sub_i32 s21, 0, s18
	v_rcp_iflag_f32_e32 v2, v2
	s_abs_i32 s14, s15
	s_xor_b32 s19, s15, s17
	s_ashr_i32 s19, s19, 31
	v_mul_f32_e32 v2, 0x4f7ffffe, v2
	v_cvt_u32_f32_e32 v2, v2
	s_nop 0
	v_readfirstlane_b32 s30, v2
	s_mul_i32 s21, s21, s30
	s_mul_hi_u32 s21, s30, s21
	s_add_i32 s30, s30, s21
	s_mul_hi_u32 s21, s14, s30
	s_mul_i32 s30, s21, s18
	s_sub_i32 s14, s14, s30
	s_add_i32 s50, s21, 1
	s_sub_i32 s30, s14, s18
	s_cmp_ge_u32 s14, s18
	s_cselect_b32 s21, s50, s21
	s_cselect_b32 s14, s30, s14
	s_add_i32 s30, s21, 1
	s_cmp_ge_u32 s14, s18
	s_cselect_b32 s14, s30, s21
	s_xor_b32 s14, s14, s19
	s_sub_i32 s14, s14, s19
	s_mul_i32 s17, s14, s17
	s_sub_i32 s15, s15, s17
	s_add_i32 s30, s16, s15
